# dppsum: x->bf16 conversion loop row sum via DPP moves + permlane swaps instead of 6 ds_bpermute round trips per row (on top of silupk+cumsumlds+ffwide+swapred)
# speedup vs baseline: 1.0020x; 1.0020x over previous
; __device__ __forceinline__ unsigned cvt_pk_bf16(float lo, float hi) { const f32x2cv v = {lo, hi}; const bf16x2cv b = __builtin_convertvector(v, bf16x2cv); return __builtin_bit_cast(unsigned, b); }
; __device__ __forceinline__ float wave_sum(float v) {
; #pragma unroll
;     for (int o = 1; o < 64; o <<= 1) v += __shfl_xor(v, o);
;     return v;
; }
; __device__ __forceinline__ void row_to_bf16(const float* xrow, bf16* orow, float* ssqrow, bool normalise, int lane) {
;     const f32x4* xr = (const f32x4*)xrow + lane; f32x4 v[4]; float s = 0.f;
; #pragma unroll
;     for (int j = 0; j < 4; ++j) { v[j] = xr[64 * j]; s += (v[j][0] * v[j][0] + v[j][1] * v[j][1]) + (v[j][2] * v[j][2] + v[j][3] * v[j][3]); }
;     s = wave_sum(s);
;     const float rs = normalise ? 1.0f / sqrtf(s * (1.f / DM) + EPS) : 1.f;
;     v2u* o8 = (v2u*)orow + lane;
; #pragma unroll
;     for (int j = 0; j < 4; ++j) { v2u w; w.x = cvt_pk_bf16(v[j][0] * rs, v[j][1] * rs); w.y = cvt_pk_bf16(v[j][2] * rs, v[j][3] * rs); o8[64 * j] = w; }
;     if (ssqrow && lane < 16) ssqrow[lane] = (lane == 0) ? s : 0.f;
.LBB0_56:
	s_waitcnt lgkmcnt(0)
	global_load_dwordx4 v[14:17], v[4:5], off offset:-3072
	global_load_dwordx4 v[22:25], v[4:5], off offset:-2048
	global_load_dwordx4 v[26:29], v[4:5], off offset:-1024
	global_load_dwordx4 v[30:33], v[4:5], off
	s_mov_b32 s6, 0x3a00000
	s_waitcnt vmcnt(0)
	v_mul_f32_e32 v13, v15, v15
	v_mul_f32_e32 v18, v17, v17
	v_mul_f32_e32 v19, v23, v23
	v_mul_f32_e32 v21, v25, v25
	v_mul_f32_e32 v34, v27, v27
	v_mul_f32_e32 v35, v29, v29
	v_fmac_f32_e32 v13, v14, v14
	v_fmac_f32_e32 v18, v16, v16
	v_fmac_f32_e32 v19, v22, v22
	v_fmac_f32_e32 v21, v24, v24
	v_mul_f32_e32 v36, v31, v31
	v_mul_f32_e32 v37, v33, v33
	v_fmac_f32_e32 v34, v26, v26
	v_fmac_f32_e32 v35, v28, v28
	v_add_f32_e32 v13, v13, v18
	v_add_f32_e32 v18, v19, v21
	v_fmac_f32_e32 v36, v30, v30
	v_fmac_f32_e32 v37, v32, v32
	v_add_f32_e32 v19, v34, v35
	v_add_f32_e32 v13, v13, v18
	v_add_f32_e32 v21, v36, v37
	v_add_f32_e32 v13, v13, v19
	v_add_f32_e32 v13, v13, v21
	s_nop 1
	v_mov_b32_dpp v18, v13 quad_perm:[1,0,3,2] row_mask:0xf bank_mask:0xf
	v_cvt_pk_bf16_f32 v14, v14, v15
	v_cvt_pk_bf16_f32 v15, v16, v17
	v_cvt_pk_bf16_f32 v16, v22, v23
	v_cvt_pk_bf16_f32 v17, v24, v25
	s_waitcnt lgkmcnt(0)
	v_add_f32_e32 v13, v13, v18
	s_nop 1
	v_mov_b32_dpp v18, v13 quad_perm:[2,3,0,1] row_mask:0xf bank_mask:0xf
	v_cvt_pk_bf16_f32 v22, v26, v27
	v_cvt_pk_bf16_f32 v23, v28, v29
	s_waitcnt lgkmcnt(0)
	v_add_f32_e32 v13, v13, v18
	s_nop 1
	v_mov_b32_dpp v21, v13 row_half_mirror row_mask:0xf bank_mask:0xf
	v_lshl_add_u64 v[18:19], s[10:11], 0, v[2:3]
	v_add_co_u32_e64 v18, s[6:7], s6, v18
	s_waitcnt lgkmcnt(0)
	v_add_f32_e32 v13, v13, v21
	s_nop 1
	v_mov_b32_dpp v21, v13 row_ror:8 row_mask:0xf bank_mask:0xf
	v_addc_co_u32_e64 v19, s[6:7], 0, v19, s[6:7]
	flat_store_dwordx2 v[18:19], v[14:15]
	flat_store_dwordx2 v[18:19], v[16:17] offset:512
	v_cvt_pk_bf16_f32 v16, v30, v31
	s_waitcnt lgkmcnt(0)
	v_add_f32_e32 v13, v13, v21
	v_mov_b32_e32 v21, v13
	s_nop 1
	v_permlane16_swap_b32_e32 v13, v21
	v_cvt_pk_bf16_f32 v17, v32, v33
	flat_store_dwordx2 v[18:19], v[22:23] offset:1024
	flat_store_dwordx2 v[18:19], v[16:17] offset:1536
	s_waitcnt lgkmcnt(0)
	v_add_f32_e32 v13, v13, v21
	v_mov_b32_e32 v14, v13
	s_nop 1
	v_permlane32_swap_b32_e32 v13, v14
	s_and_saveexec_b64 s[6:7], vcc
	s_cbranch_execz .LBB0_55
	s_waitcnt lgkmcnt(0)
	v_add_f32_e32 v13, v13, v14
	v_lshl_add_u64 v[16:17], s[10:11], 0, v[0:1]
	v_cndmask_b32_e64 v13, 0, v13, s[4:5]
	flat_store_dword v[16:17], v13
	s_branch .LBB0_55
